# latent attention PV: the four V^T fragment LDS reads of a k-step issued together (3 extra quads borrowed from scheduler-constant VGPRs, re-materialised after the block loop), MFMAs behind counted lgkm
# baseline (speedup 1.0000x reference)
.LBB0_387:
	v_lshl_add_u32 v18, s18, 7, v145
	s_waitcnt vmcnt(2)
	ds_write_b128 v136, v[4:7] offset:640
	s_waitcnt vmcnt(1)
	ds_write_b128 v136, v[8:11] offset:768
	s_waitcnt vmcnt(0)
	ds_write_b128 v136, v[12:15] offset:896
	s_waitcnt lgkmcnt(0)
	s_barrier
	v_cvt_pk_bf16_f32 v4, v166, v165
	v_cvt_pk_bf16_f32 v5, v168, v167
	v_cvt_pk_bf16_f32 v6, v171, v230
	v_cvt_pk_bf16_f32 v7, v172, v231
	ds_read_b128 v[8:11], v18
	ds_read_b128 v[12:15], v18 offset:18688
	ds_read_b128 v[114:117], v18 offset:37376
	ds_read_b128 v[164:167], v18 offset:56064
	v_lshl_add_u32 v18, s19, 7, v145
	s_waitcnt lgkmcnt(3)
	v_mfma_f32_16x16x32_bf16 v[8:11], v[8:11], v[4:7], 0
	v_lshlrev_b64 v[16:17], 11, v[16:17]
	v_lshl_add_u64 v[16:17], v[60:61], 0, v[16:17]
	s_addk_i32 s6, 0x80
	s_waitcnt lgkmcnt(2)
	v_mfma_f32_16x16x32_bf16 v[12:15], v[12:15], v[4:7], 0
	s_add_i32 s79, s79, 2
	s_add_i32 s80, s80, 2
	s_add_i32 s81, s81, -2
	s_waitcnt lgkmcnt(1)
	v_mfma_f32_16x16x32_bf16 v[114:117], v[114:117], v[4:7], 0
	s_cmpk_lg_i32 s6, 0x800
	s_waitcnt lgkmcnt(0)
	v_mfma_f32_16x16x32_bf16 v[4:7], v[164:167], v[4:7], 0
	v_cvt_pk_bf16_f32 v164, v169, v170
	v_cvt_pk_bf16_f32 v165, v173, v174
	v_cvt_pk_bf16_f32 v166, v175, v177
	v_cvt_pk_bf16_f32 v167, v179, v232
	ds_read_b128 v[168:171], v18
	ds_read_b128 v[152:155], v18 offset:18688
	ds_read_b128 v[156:159], v18 offset:37376
	ds_read_b128 v[160:163], v18 offset:56064
	v_lshl_add_u32 v18, s20, 7, v145
	s_waitcnt lgkmcnt(3)
	v_mfma_f32_16x16x32_bf16 v[8:11], v[168:171], v[164:167], v[8:11]
	s_waitcnt lgkmcnt(2)
	v_mfma_f32_16x16x32_bf16 v[12:15], v[152:155], v[164:167], v[12:15]
	s_waitcnt lgkmcnt(1)
	v_mfma_f32_16x16x32_bf16 v[114:117], v[156:159], v[164:167], v[114:117]
	s_waitcnt lgkmcnt(0)
	v_mfma_f32_16x16x32_bf16 v[4:7], v[160:163], v[164:167], v[4:7]
	v_cvt_pk_bf16_f32 v164, v176, v178
	v_cvt_pk_bf16_f32 v165, v180, v181
	v_cvt_pk_bf16_f32 v166, v182, v184
	v_cvt_pk_bf16_f32 v167, v187, v189
	ds_read_b128 v[168:171], v18
	ds_read_b128 v[152:155], v18 offset:18688
	ds_read_b128 v[156:159], v18 offset:37376
	ds_read_b128 v[160:163], v18 offset:56064
	v_lshl_add_u32 v18, s21, 7, v145
	s_waitcnt lgkmcnt(3)
	v_mfma_f32_16x16x32_bf16 v[8:11], v[168:171], v[164:167], v[8:11]
	s_waitcnt lgkmcnt(2)
	v_mfma_f32_16x16x32_bf16 v[12:15], v[152:155], v[164:167], v[12:15]
	s_waitcnt lgkmcnt(1)
	v_mfma_f32_16x16x32_bf16 v[114:117], v[156:159], v[164:167], v[114:117]
	s_waitcnt lgkmcnt(0)
	v_mfma_f32_16x16x32_bf16 v[4:7], v[160:163], v[164:167], v[4:7]
	v_cvt_pk_bf16_f32 v164, v183, v185
	v_cvt_pk_bf16_f32 v165, v186, v190
	v_cvt_pk_bf16_f32 v166, v191, v193
	v_cvt_pk_bf16_f32 v167, v196, v197
	ds_read_b128 v[168:171], v18
	ds_read_b128 v[152:155], v18 offset:18688
	ds_read_b128 v[156:159], v18 offset:37376
	ds_read_b128 v[160:163], v18 offset:56064
	v_lshl_add_u32 v18, s30, 7, v145
	s_waitcnt lgkmcnt(3)
	v_mfma_f32_16x16x32_bf16 v[8:11], v[168:171], v[164:167], v[8:11]
	s_waitcnt lgkmcnt(2)
	v_mfma_f32_16x16x32_bf16 v[12:15], v[152:155], v[164:167], v[12:15]
	s_waitcnt lgkmcnt(1)
	v_mfma_f32_16x16x32_bf16 v[114:117], v[156:159], v[164:167], v[114:117]
	s_waitcnt lgkmcnt(0)
	v_mfma_f32_16x16x32_bf16 v[4:7], v[160:163], v[164:167], v[4:7]
	v_cvt_pk_bf16_f32 v164, v192, v194
	v_cvt_pk_bf16_f32 v165, v195, v198
	v_cvt_pk_bf16_f32 v166, v199, v201
	v_cvt_pk_bf16_f32 v167, v204, v205
	ds_read_b128 v[168:171], v18
	ds_read_b128 v[152:155], v18 offset:18688
	ds_read_b128 v[156:159], v18 offset:37376
	ds_read_b128 v[160:163], v18 offset:56064
	v_lshl_add_u32 v18, s31, 7, v145
	s_waitcnt lgkmcnt(3)
	v_mfma_f32_16x16x32_bf16 v[8:11], v[168:171], v[164:167], v[8:11]
	s_waitcnt lgkmcnt(2)
	v_mfma_f32_16x16x32_bf16 v[12:15], v[152:155], v[164:167], v[12:15]
	s_waitcnt lgkmcnt(1)
	v_mfma_f32_16x16x32_bf16 v[114:117], v[156:159], v[164:167], v[114:117]
	s_waitcnt lgkmcnt(0)
	v_mfma_f32_16x16x32_bf16 v[4:7], v[160:163], v[164:167], v[4:7]
	v_cvt_pk_bf16_f32 v164, v200, v202
	v_cvt_pk_bf16_f32 v165, v203, v206
	v_cvt_pk_bf16_f32 v166, v207, v209
	v_cvt_pk_bf16_f32 v167, v212, v233
	ds_read_b128 v[168:171], v18
	ds_read_b128 v[152:155], v18 offset:18688
	ds_read_b128 v[156:159], v18 offset:37376
	ds_read_b128 v[160:163], v18 offset:56064
	v_lshl_add_u32 v18, s33, 7, v145
	s_waitcnt lgkmcnt(3)
	v_mfma_f32_16x16x32_bf16 v[8:11], v[168:171], v[164:167], v[8:11]
	s_waitcnt lgkmcnt(2)
	v_mfma_f32_16x16x32_bf16 v[12:15], v[152:155], v[164:167], v[12:15]
	s_waitcnt lgkmcnt(1)
	v_mfma_f32_16x16x32_bf16 v[114:117], v[156:159], v[164:167], v[114:117]
	s_waitcnt lgkmcnt(0)
	v_mfma_f32_16x16x32_bf16 v[4:7], v[160:163], v[164:167], v[4:7]
	v_cvt_pk_bf16_f32 v164, v208, v210
	v_cvt_pk_bf16_f32 v165, v211, v214
	v_cvt_pk_bf16_f32 v166, v215, v217
	v_cvt_pk_bf16_f32 v167, v220, v234
	ds_read_b128 v[168:171], v18
	ds_read_b128 v[152:155], v18 offset:18688
	ds_read_b128 v[156:159], v18 offset:37376
	ds_read_b128 v[160:163], v18 offset:56064
	v_lshl_add_u32 v18, s34, 7, v145
	s_waitcnt lgkmcnt(3)
	v_mfma_f32_16x16x32_bf16 v[8:11], v[168:171], v[164:167], v[8:11]
	s_waitcnt lgkmcnt(2)
	v_mfma_f32_16x16x32_bf16 v[12:15], v[152:155], v[164:167], v[12:15]
	s_waitcnt lgkmcnt(1)
	v_mfma_f32_16x16x32_bf16 v[114:117], v[156:159], v[164:167], v[114:117]
	s_waitcnt lgkmcnt(0)
	v_mfma_f32_16x16x32_bf16 v[4:7], v[160:163], v[164:167], v[4:7]
	v_cvt_pk_bf16_f32 v164, v213, v216
	v_cvt_pk_bf16_f32 v165, v218, v221
	v_cvt_pk_bf16_f32 v166, v222, v224
	v_cvt_pk_bf16_f32 v167, v226, v229
	ds_read_b128 v[168:171], v18
	ds_read_b128 v[152:155], v18 offset:18688
	ds_read_b128 v[156:159], v18 offset:37376
	ds_read_b128 v[160:163], v18 offset:56064
	s_waitcnt lgkmcnt(3)
	v_mfma_f32_16x16x32_bf16 v[8:11], v[168:171], v[164:167], v[8:11]
	s_waitcnt lgkmcnt(2)
	v_mfma_f32_16x16x32_bf16 v[12:15], v[152:155], v[164:167], v[12:15]
	s_waitcnt lgkmcnt(1)
	v_mfma_f32_16x16x32_bf16 v[114:117], v[156:159], v[164:167], v[114:117]
	s_waitcnt lgkmcnt(0)
	v_mfma_f32_16x16x32_bf16 v[4:7], v[160:163], v[164:167], v[4:7]
	v_cvt_pk_bf16_f32 v164, v219, v223
	v_cvt_pk_bf16_f32 v165, v225, v227
	v_cvt_pk_bf16_f32 v166, v228, v235
	v_cvt_pk_bf16_f32 v167, v236, v237
	ds_read_b128 v[168:171], v135 offset:36864
	ds_read_b128 v[152:155], v135 offset:45312
	ds_read_b128 v[156:159], v135 offset:53760
	ds_read_b128 v[160:163], v135 offset:62208
	s_waitcnt lgkmcnt(3)
	v_mfma_f32_16x16x32_bf16 v[8:11], v[168:171], v[164:167], v[8:11]
	s_waitcnt lgkmcnt(2)
	v_mfma_f32_16x16x32_bf16 v[12:15], v[152:155], v[164:167], v[12:15]
	s_waitcnt lgkmcnt(1)
	v_mfma_f32_16x16x32_bf16 v[114:117], v[156:159], v[164:167], v[114:117]
	s_waitcnt lgkmcnt(0)
	v_mfma_f32_16x16x32_bf16 v[4:7], v[160:163], v[164:167], v[4:7]
	v_cvt_pk_bf16_f32 v164, v22, v23
	v_cvt_pk_bf16_f32 v165, v20, v26
	v_cvt_pk_bf16_f32 v166, v27, v30
	v_cvt_pk_bf16_f32 v167, v31, v238
	ds_read_b128 v[168:171], v135 offset:36928
	s_waitcnt lgkmcnt(0)
	v_mfma_f32_16x16x32_bf16 v[8:11], v[168:171], v[164:167], v[8:11]
	ds_read_b128 v[168:171], v135 offset:45376
	s_waitcnt lgkmcnt(0)
	v_mfma_f32_16x16x32_bf16 v[12:15], v[168:171], v[164:167], v[12:15]
	ds_read_b128 v[168:171], v135 offset:53824
	s_waitcnt lgkmcnt(0)
	v_mfma_f32_16x16x32_bf16 v[114:117], v[168:171], v[164:167], v[114:117]
	ds_read_b128 v[168:171], v135 offset:62272
	v_cvt_pk_bf16_f32 v18, v21, v24
	v_cvt_pk_bf16_f32 v19, v25, v28
	v_cvt_pk_bf16_f32 v20, v34, v35
	v_cvt_pk_bf16_f32 v21, v82, v83
	ds_read_b128 v[22:25], v135 offset:36992
	s_waitcnt lgkmcnt(0)
	v_mfma_f32_16x16x32_bf16 v[8:11], v[22:25], v[18:21], v[8:11]
	ds_read_b128 v[22:25], v135 offset:45440
	s_waitcnt lgkmcnt(0)
	v_mfma_f32_16x16x32_bf16 v[12:15], v[22:25], v[18:21], v[12:15]
	ds_read_b128 v[22:25], v135 offset:53888
	s_waitcnt lgkmcnt(0)
	v_mfma_f32_16x16x32_bf16 v[22:25], v[22:25], v[18:21], v[114:117]
	s_nop 2
	ds_read_b128 v[114:117], v135 offset:62336
	v_mfma_f32_16x16x32_bf16 v[4:7], v[168:171], v[164:167], v[4:7]
	s_waitcnt lgkmcnt(0)
	v_mfma_f32_16x16x32_bf16 v[4:7], v[114:117], v[18:21], v[4:7]
	v_cvt_pk_bf16_f32 v18, v29, v32
	v_cvt_pk_bf16_f32 v19, v33, v80
	v_cvt_pk_bf16_f32 v20, v86, v87
	v_cvt_pk_bf16_f32 v21, v91, v239
	ds_read_b128 v[26:29], v135 offset:37056
	ds_read_b128 v[152:155], v135 offset:45504
	ds_read_b128 v[156:159], v135 offset:53952
	ds_read_b128 v[160:163], v135 offset:62400
	s_waitcnt lgkmcnt(3)
	v_mfma_f32_16x16x32_bf16 v[8:11], v[26:29], v[18:21], v[8:11]
	s_waitcnt lgkmcnt(2)
	v_mfma_f32_16x16x32_bf16 v[12:15], v[152:155], v[18:21], v[12:15]
	s_waitcnt lgkmcnt(1)
	v_mfma_f32_16x16x32_bf16 v[22:25], v[156:159], v[18:21], v[22:25]
	s_waitcnt lgkmcnt(0)
	v_mfma_f32_16x16x32_bf16 v[4:7], v[160:163], v[18:21], v[4:7]
	v_cvt_pk_bf16_f32 v18, v81, v84
	v_cvt_pk_bf16_f32 v19, v90, v89
	v_cvt_pk_bf16_f32 v20, v94, v98
	v_cvt_pk_bf16_f32 v21, v240, v242
	ds_read_b128 v[26:29], v135 offset:37120
	ds_read_b128 v[152:155], v135 offset:45568
	ds_read_b128 v[156:159], v135 offset:54016
	ds_read_b128 v[160:163], v135 offset:62464
	s_waitcnt lgkmcnt(3)
	v_mfma_f32_16x16x32_bf16 v[8:11], v[26:29], v[18:21], v[8:11]
	s_waitcnt lgkmcnt(2)
	v_mfma_f32_16x16x32_bf16 v[12:15], v[152:155], v[18:21], v[12:15]
	s_waitcnt lgkmcnt(1)
	v_mfma_f32_16x16x32_bf16 v[22:25], v[156:159], v[18:21], v[22:25]
	s_waitcnt lgkmcnt(0)
	v_mfma_f32_16x16x32_bf16 v[4:7], v[160:163], v[18:21], v[4:7]
	v_cvt_pk_bf16_f32 v18, v92, v93
	v_cvt_pk_bf16_f32 v19, v102, v241
	v_cvt_pk_bf16_f32 v20, v243, v244
	v_cvt_pk_bf16_f32 v21, v245, v246
	ds_read_b128 v[26:29], v135 offset:37184
	ds_read_b128 v[152:155], v135 offset:45632
	ds_read_b128 v[156:159], v135 offset:54080
	ds_read_b128 v[160:163], v135 offset:62528
	s_waitcnt lgkmcnt(3)
	v_mfma_f32_16x16x32_bf16 v[8:11], v[26:29], v[18:21], v[8:11]
	s_waitcnt lgkmcnt(2)
	v_mfma_f32_16x16x32_bf16 v[12:15], v[152:155], v[18:21], v[12:15]
	s_waitcnt lgkmcnt(1)
	v_mfma_f32_16x16x32_bf16 v[22:25], v[156:159], v[18:21], v[22:25]
	s_waitcnt lgkmcnt(0)
	v_mfma_f32_16x16x32_bf16 v[4:7], v[160:163], v[18:21], v[4:7]
	v_cvt_pk_bf16_f32 v18, v105, v108
	v_cvt_pk_bf16_f32 v19, v106, v107
	v_cvt_pk_bf16_f32 v20, v109, v112
	v_cvt_pk_bf16_f32 v21, v110, v111
	ds_read_b128 v[26:29], v135 offset:37248
	ds_read_b128 v[152:155], v135 offset:45696
	ds_read_b128 v[156:159], v135 offset:54144
	ds_read_b128 v[160:163], v135 offset:62592
	s_waitcnt lgkmcnt(3)
	v_mfma_f32_16x16x32_bf16 v[8:11], v[26:29], v[18:21], v[8:11]
	s_waitcnt lgkmcnt(2)
	v_mfma_f32_16x16x32_bf16 v[12:15], v[152:155], v[18:21], v[12:15]
	s_waitcnt lgkmcnt(1)
	v_mfma_f32_16x16x32_bf16 v[22:25], v[156:159], v[18:21], v[22:25]
	s_waitcnt lgkmcnt(0)
	v_mfma_f32_16x16x32_bf16 v[4:7], v[160:163], v[18:21], v[4:7]
	v_cvt_pk_bf16_f32 v18, v95, v97
	v_cvt_pk_bf16_f32 v19, v96, v99
	v_cvt_pk_bf16_f32 v20, v100, v101
	v_cvt_pk_bf16_f32 v21, v103, v104
	ds_read_b128 v[26:29], v135 offset:37312
	ds_read_b128 v[152:155], v135 offset:45760
	ds_read_b128 v[156:159], v135 offset:54208
	ds_read_b128 v[160:163], v135 offset:62656
	s_waitcnt lgkmcnt(3)
	v_mfma_f32_16x16x32_bf16 v[8:11], v[26:29], v[18:21], v[8:11]
	s_waitcnt lgkmcnt(2)
	v_mfma_f32_16x16x32_bf16 v[12:15], v[152:155], v[18:21], v[12:15]
	s_waitcnt lgkmcnt(1)
	v_mfma_f32_16x16x32_bf16 v[22:25], v[156:159], v[18:21], v[22:25]
	s_waitcnt lgkmcnt(0)
	v_mfma_f32_16x16x32_bf16 v[4:7], v[160:163], v[18:21], v[4:7]
	v_add_f32_e32 v18, v85, v88
	v_div_scale_f32 v19, s[16:17], v18, v18, 1.0
	v_rcp_f32_e32 v20, v19
	s_nop 0
	v_fma_f32 v21, -v19, v20, 1.0
	v_fmac_f32_e32 v20, v21, v20
	v_div_scale_f32 v21, vcc, 1.0, v18, 1.0
	v_mul_f32_e32 v26, v21, v20
	v_fma_f32 v27, -v19, v26, v21
	v_fmac_f32_e32 v26, v27, v20
	v_fma_f32 v19, -v19, v26, v21
	v_div_fmas_f32 v19, v19, v20, v26
	v_div_fixup_f32 v18, v19, v18, 1.0
	v_pk_mul_f32 v[10:11], v[18:19], v[10:11] op_sel_hi:[0,1]
	v_pk_mul_f32 v[8:9], v[18:19], v[8:9] op_sel_hi:[0,1]
	v_cvt_pk_bf16_f32 v8, v8, v9
	v_cvt_pk_bf16_f32 v9, v10, v11
	v_pk_mul_f32 v[10:11], v[18:19], v[12:13] op_sel_hi:[0,1]
	global_store_dwordx2 v[16:17], v[8:9], off
	v_pk_mul_f32 v[8:9], v[18:19], v[14:15] op_sel_hi:[0,1]
	v_cvt_pk_bf16_f32 v10, v10, v11
	v_cvt_pk_bf16_f32 v11, v8, v9
	global_store_dwordx2 v[16:17], v[10:11], off offset:32
	v_pk_mul_f32 v[10:11], v[18:19], v[22:23] op_sel_hi:[0,1]
	v_pk_mul_f32 v[4:5], v[18:19], v[4:5] op_sel_hi:[0,1]
	v_pk_mul_f32 v[8:9], v[18:19], v[24:25] op_sel_hi:[0,1]
	v_cvt_pk_bf16_f32 v10, v10, v11
	v_cvt_pk_bf16_f32 v11, v8, v9
	global_store_dwordx2 v[16:17], v[10:11], off offset:64
	v_pk_mul_f32 v[6:7], v[18:19], v[6:7] op_sel_hi:[0,1]
	v_cvt_pk_bf16_f32 v4, v4, v5
	v_cvt_pk_bf16_f32 v5, v6, v7
	global_store_dwordx2 v[16:17], v[4:5], off offset:96
	s_cbranch_scc0 .LBB0_375

.LBB0_522:
	v_mov_b64_e32 v[152:153], 0x240
	v_mov_b64_e32 v[154:155], 0x23f
	v_mov_b64_e32 v[156:157], 0x7e0
	v_mov_b64_e32 v[158:159], 0x7df
	v_mov_b64_e32 v[160:161], 0x6c0
	v_mov_b64_e32 v[162:163], 0x6bf
	s_lshl_b32 s0, s57, 3
	s_add_i32 s2, s0, s56
	v_readlane_b32 s70, v255, 11
	v_readlane_b32 s30, v255, 13
	v_readlane_b32 s34, v255, 15
	v_readlane_b32 s38, v255, 17
	s_cmpk_gt_i32 s2, 0xfff
	v_readlane_b32 s78, v255, 5
	v_readlane_b32 s72, v255, 6
	v_readlane_b32 s71, v255, 12
	v_readlane_b32 s31, v255, 14
	v_readlane_b32 s35, v255, 16
	v_readlane_b32 s39, v255, 18
	s_mov_b64 s[74:75], 0xc80000
	s_waitcnt vmcnt(0) lgkmcnt(0)
	s_barrier
	v_readlane_b32 s73, v255, 7
	s_cbranch_scc1 .LBB0_525
	v_mul_u32_u24_e32 v0, 0x9000, v118
	v_and_b32_e32 v1, 64, v188
	v_add_lshl_u32 v32, v0, v36, 1
	v_xor_b32_e32 v0, 16, v188
	v_add_u32_e32 v1, 64, v1
	v_cmp_lt_i32_e32 vcc, v0, v1
	v_xor_b32_e32 v2, 32, v188
	s_lshl_b32 s0, s57, 5
	v_cndmask_b32_e32 v0, v188, v0, vcc
	v_cmp_lt_i32_e32 vcc, v2, v1
	s_lshl_b32 s1, s56, 2
	s_add_i32 s4, s0, s1
	v_cndmask_b32_e32 v1, v188, v2, vcc
	s_lshl_b32 s0, s57, 7
	s_lshl_b32 s1, s56, 4
	s_lshl_b32 s3, s10, 3
	v_lshl_add_u32 v148, v47, 12, v51
	v_mov_b32_e32 v33, v149
	v_lshlrev_b32_e32 v78, 2, v0
	v_lshlrev_b32_e32 v79, 2, v1
	s_lshl_b32 s5, s10, 5
	s_add_i32 s11, s0, s1
	s_lshl_b32 s10, s10, 7
	s_mov_b32 s19, 0x40000
	s_mov_b32 s20, 0x120000
